# NA score-modifier rewrite (batched LUT reads, branch-free select) + software-pipelined final-norm row loop
# speedup vs baseline: 1.0031x; 1.0031x over previous
; #define SBAR() __builtin_amdgcn_sched_barrier(0)
; template <int MODE> __device__ __forceinline__ float apply_mode(f32x16& p0, f32x16& p1, int t, const ModeCtx& c, const LAS float* lut, int hi) {
;     ...
;     } else if constexpr (MODE == 3) {
;         const int ki = c.krow0 + t;
;         const bool rowok = (unsigned)(ki - c.rs) < 8u;
;         const int base = (ki - c.qi + 7) * 31 + 15 - c.qj + 4 * hi;
;         const int kjb = 4 * hi - c.cs;
; #pragma unroll
;         for (int r = 0; r < 16; ++r) {
;             const int kj0 = (r & 3) + 8 * (r >> 2);
;             const bool ok0 = rowok && ((unsigned)(kjb + kj0) < 16u), ok1 = rowok && ((unsigned)(kjb + kj0 + 32) < 16u);
;             const float v0 = lut[ok0 ? base + kj0 : 0], v1 = lut[ok1 ? base + kj0 + 32 : 0];
;             p0[r] = ok0 ? p0[r] + v0 : -INFINITY; p1[r] = ok1 ? p1[r] + v1 : -INFINITY;
;         }
; template <int MODE, int VW>
; __device__ __forceinline__ void attn_unit_s(const AttnP& P, char* lds, const int tid) {
;     ...
;     for (int j = 0; j < NT; ++j) {
;         const int b = j & 1;
;         if (j + 1 < NT) BDMA(b ^ 1, (j + 1) * KVBLK);
;         if (j >= t_lo && j < t_hi) {
;         f32x16 p0, p1; float mn, alpha; bf16x8 pa0, pa1, pa2, pa3;
;         SBAR(); qkt<QLD>(p0, p1, K_lds + b * SHM_K, qr, qlds, r32, hi);
;         const float cb_ = apply_mode<MODE>(p0, p1, j, mc, lut, hi); partialSM(p0, p1, m_reg, mn, alpha, cb_);
.LBB0_1613:
	s_and_b32 s3, s9, 1
	s_lshl_b32 s2, s3, 14
	s_xor_b32 s11, s2, 0x4000
	s_add_i32 s11, s8, s11
	v_lshl_add_u64 v[66:67], s[0:1], 0, v[148:149]
	s_mov_b32 m0, s11
	s_nop 0
	global_load_lds_dwordx4 v[66:67], off
	s_add_i32 m0, s11, 0x2000
	s_lshl_b32 s11, s3, 15
	s_xor_b32 s3, s11, 0x8000
	v_lshl_add_u64 v[66:67], s[0:1], 0, v[150:151]
	s_add_i32 s3, s7, s3
	global_load_lds_dwordx4 v[66:67], off
	v_lshl_add_u64 v[66:67], s[0:1], 0, v[146:147]
	s_mov_b32 m0, s3
	s_nop 0
	global_load_lds_dwordx4 v[66:67], off
	v_lshl_add_u64 v[66:67], s[0:1], 0, v[144:145]
	s_add_i32 m0, s3, 0x2000
	s_cmp_ge_i32 s9, s5
	global_load_lds_dwordx4 v[66:67], off
	s_cselect_b64 s[68:69], -1, 0
	s_cmp_lt_i32 s9, s6
	s_cselect_b64 s[70:71], -1, 0
	s_and_b64 s[68:69], s[68:69], s[70:71]
	s_andn2_b64 vcc, exec, s[68:69]
	s_cbranch_vccnz .LBB0_1612
	s_add_i32 s2, s2, 0
	s_add_i32 s2, s2, 0x10000
	v_add3_u32 v0, s2, v170, v161
	ds_read_b128 v[66:69], v0
	ds_read_b128 v[70:73], v0 offset:8192
	v_add3_u32 v0, s2, v168, v161
	ds_read_b128 v[174:177], v0
	ds_read_b128 v[178:181], v0 offset:8192
	v_add3_u32 v0, s2, v167, v161
	s_waitcnt lgkmcnt(0)
	v_mfma_f32_32x32x16_bf16 v[82:97], v[66:69], v[134:137], 0
	v_mov_b32_e32 v173, 0xff800000
	v_mfma_f32_32x32x16_bf16 v[66:81], v[70:73], v[134:137], 0
	v_mfma_f32_32x32x16_bf16 v[82:97], v[174:177], v[130:133], v[82:97]
	v_mfma_f32_32x32x16_bf16 v[66:81], v[178:181], v[130:133], v[66:81]
	ds_read_b128 v[174:177], v0
	ds_read_b128 v[178:181], v0 offset:8192
	v_add3_u32 v0, s2, v166, v161
	s_waitcnt lgkmcnt(0)
	v_mfma_f32_32x32x16_bf16 v[82:97], v[174:177], v[126:129], v[82:97]
	v_mfma_f32_32x32x16_bf16 v[66:81], v[178:181], v[126:129], v[66:81]
	ds_read_b128 v[174:177], v0
	ds_read_b128 v[178:181], v0 offset:8192
	v_add3_u32 v0, s2, v165, v161
	s_waitcnt lgkmcnt(0)
	v_mfma_f32_32x32x16_bf16 v[82:97], v[174:177], v[122:125], v[82:97]
	v_mfma_f32_32x32x16_bf16 v[66:81], v[178:181], v[122:125], v[66:81]
	ds_read_b128 v[174:177], v0
	ds_read_b128 v[178:181], v0 offset:8192
	v_add3_u32 v0, s2, v164, v161
	s_waitcnt lgkmcnt(0)
	v_mfma_f32_32x32x16_bf16 v[82:97], v[174:177], v[118:121], v[82:97]
	v_mfma_f32_32x32x16_bf16 v[66:81], v[178:181], v[118:121], v[66:81]
	ds_read_b128 v[174:177], v0
	ds_read_b128 v[178:181], v0 offset:8192
	v_add3_u32 v0, s2, v163, v161
	s_waitcnt lgkmcnt(0)
	v_mfma_f32_32x32x16_bf16 v[82:97], v[174:177], v[114:117], v[82:97]
	v_mfma_f32_32x32x16_bf16 v[66:81], v[178:181], v[114:117], v[66:81]
	ds_read_b128 v[174:177], v0
	ds_read_b128 v[178:181], v0 offset:8192
	v_add3_u32 v0, s2, v162, v161
	s_add_i32 s2, s10, s9
	s_cmp_lt_u32 s2, 8
	s_cselect_b64 s[2:3], -1, 0
	s_and_b64 vcc, s[2:3], s[64:65]
	s_and_b64 s[70:71], s[2:3], s[66:67]
	s_waitcnt lgkmcnt(0)
	v_mfma_f32_32x32x16_bf16 v[82:97], v[174:177], v[110:113], v[82:97]
	v_add_u32_e32 v176, s33, v172
	v_mfma_f32_32x32x16_bf16 v[66:81], v[178:181], v[110:113], v[66:81]
	ds_read_b128 v[178:181], v0
	ds_read_b128 v[182:185], v0 offset:8192
	v_lshlrev_b32_e32 v206, 2, v176
	v_add_u32_e32 v206, 0x20c20, v206
	ds_read2_b32 v[190:191], v171 offset1:1
	ds_read2_b32 v[192:193], v171 offset0:2 offset1:3
	ds_read2_b32 v[194:195], v171 offset0:8 offset1:9
	ds_read2_b32 v[196:197], v171 offset0:10 offset1:11
	ds_read2_b32 v[198:199], v171 offset0:16 offset1:17
	ds_read2_b32 v[200:201], v171 offset0:18 offset1:19
	ds_read2_b32 v[202:203], v171 offset0:24 offset1:25
	ds_read2_b32 v[204:205], v171 offset0:26 offset1:27
	ds_read2_b32 v[208:209], v206 offset1:1
	ds_read2_b32 v[210:211], v206 offset0:2 offset1:3
	ds_read2_b32 v[212:213], v206 offset0:8 offset1:9
	ds_read2_b32 v[214:215], v206 offset0:10 offset1:11
	ds_read2_b32 v[216:217], v206 offset0:16 offset1:17
	ds_read2_b32 v[218:219], v206 offset0:18 offset1:19
	ds_read2_b32 v[220:221], v206 offset0:24 offset1:25
	ds_read2_b32 v[222:223], v206 offset0:26 offset1:27
	s_waitcnt lgkmcnt(15)
	v_mfma_f32_32x32x16_bf16 v[82:97], v[178:181], v[106:109], v[82:97]
	v_mfma_f32_32x32x16_bf16 v[66:81], v[182:185], v[106:109], v[66:81]
	v_readlane_b32 s68, v254, 31
	v_readlane_b32 s69, v254, 32
	v_readlane_b32 s70, v254, 17
	v_readlane_b32 s71, v254, 18
	v_readlane_b32 s72, v254, 5
	v_readlane_b32 s73, v254, 6
	v_readlane_b32 s74, v254, 35
	v_readlane_b32 s75, v254, 36
	v_readlane_b32 s76, v254, 33
	v_readlane_b32 s77, v254, 34
	v_readlane_b32 s78, v254, 27
	v_readlane_b32 s79, v254, 28
	s_waitcnt lgkmcnt(0)
;     ...
;     float pmax = p0[0];
; #pragma unroll
;     for (int r = 1; r < 16; ++r) pmax = fmaxf(pmax, p0[r]);
; #pragma unroll
;     for (int r = 0; r < 16; ++r) pmax = fmaxf(pmax, p1[r]);
;     { auto rr = __builtin_amdgcn_permlane32_swap(__float_as_uint(pmax), __float_as_uint(pmax), false, false);
;       pmax = fmaxf(__uint_as_float(rr[0]), __uint_as_float(rr[1])) + cb; }
;     if (__builtin_expect(__all(pmax - m_reg <= THR / SCALE), 1)) { mn = m_reg; alpha = 1.f; }
;     else { mn = fmaxf(m_reg, pmax); alpha = __builtin_amdgcn_exp2f((m_reg - mn) * C); m_reg = mn; }
; template <int MODE> __device__ __forceinline__ float apply_mode(f32x16& p0, f32x16& p1, int t, const ModeCtx& c, const LAS float* lut, int hi) {
;     ...
;         for (int r = 0; r < 16; ++r) {
;             const int kj0 = (r & 3) + 8 * (r >> 2);
;             const bool ok0 = rowok && ((unsigned)(kjb + kj0) < 16u), ok1 = rowok && ((unsigned)(kjb + kj0 + 32) < 16u);
;             const float v0 = lut[ok0 ? base + kj0 : 0], v1 = lut[ok1 ? base + kj0 + 32 : 0];
;             p0[r] = ok0 ? p0[r] + v0 : -INFINITY; p1[r] = ok1 ? p1[r] + v1 : -INFINITY;
	s_and_b64 s[80:81], s[2:3], s[66:67]
	v_add_f32_e32 v190, v82, v190
	v_cndmask_b32_e64 v173, v143, v190, s[80:81]
	s_and_b64 s[82:83], s[2:3], s[60:61]
	v_add_f32_e32 v191, v83, v191
	v_cndmask_b32_e64 v0, v143, v191, s[82:83]
	s_and_b64 s[80:81], s[2:3], s[56:57]
	v_add_f32_e32 v192, v84, v192
	v_cndmask_b32_e64 v83, v143, v192, s[80:81]
	s_and_b64 s[82:83], s[2:3], s[52:53]
	v_add_f32_e32 v193, v85, v193
	v_cndmask_b32_e64 v82, v143, v193, s[82:83]
	s_and_b64 s[80:81], s[2:3], s[48:49]
	v_add_f32_e32 v194, v86, v194
	v_cndmask_b32_e64 v85, v143, v194, s[80:81]
	s_and_b64 s[82:83], s[2:3], s[42:43]
	v_add_f32_e32 v195, v87, v195
	v_cndmask_b32_e64 v84, v143, v195, s[82:83]
	s_and_b64 s[80:81], s[2:3], s[38:39]
	v_add_f32_e32 v196, v88, v196
	v_cndmask_b32_e64 v87, v143, v196, s[80:81]
	s_and_b64 s[82:83], s[2:3], s[26:27]
	v_add_f32_e32 v197, v89, v197
	v_cndmask_b32_e64 v86, v143, v197, s[82:83]
	s_and_b64 s[80:81], s[2:3], s[14:15]
	v_add_f32_e32 v198, v90, v198
	v_cndmask_b32_e64 v89, v143, v198, s[80:81]
	s_and_b64 s[82:83], s[2:3], s[68:69]
	v_add_f32_e32 v199, v91, v199
	v_cndmask_b32_e64 v88, v143, v199, s[82:83]
	s_and_b64 s[80:81], s[2:3], s[70:71]
	v_add_f32_e32 v200, v92, v200
	v_cndmask_b32_e64 v91, v143, v200, s[80:81]
	s_and_b64 s[82:83], s[2:3], s[72:73]
	v_add_f32_e32 v201, v93, v201
	v_cndmask_b32_e64 v90, v143, v201, s[82:83]
	s_and_b64 s[80:81], s[2:3], s[20:21]
	v_add_f32_e32 v202, v94, v202
	v_cndmask_b32_e64 v93, v143, v202, s[80:81]
	s_and_b64 s[82:83], s[2:3], s[34:35]
	v_add_f32_e32 v203, v95, v203
	v_cndmask_b32_e64 v92, v143, v203, s[82:83]
	s_and_b64 s[80:81], s[2:3], s[22:23]
	v_add_f32_e32 v204, v96, v204
	v_cndmask_b32_e64 v95, v143, v204, s[80:81]
	s_and_b64 s[82:83], s[2:3], s[74:75]
	v_add_f32_e32 v205, v97, v205
	v_cndmask_b32_e64 v94, v143, v205, s[82:83]
	s_and_b64 s[80:81], s[2:3], s[64:65]
	v_add_f32_e32 v208, v66, v208
	v_cndmask_b32_e64 v97, v143, v208, s[80:81]
	s_and_b64 s[82:83], s[2:3], s[62:63]
	v_add_f32_e32 v209, v67, v209
	v_cndmask_b32_e64 v96, v143, v209, s[82:83]
	s_and_b64 s[80:81], s[2:3], s[58:59]
	v_add_f32_e32 v210, v68, v210
	v_cndmask_b32_e64 v68, v143, v210, s[80:81]
	s_and_b64 s[82:83], s[2:3], s[54:55]
	v_add_f32_e32 v211, v69, v211
	v_cndmask_b32_e64 v69, v143, v211, s[82:83]
	s_and_b64 s[80:81], s[2:3], s[50:51]
	v_add_f32_e32 v212, v70, v212
	v_cndmask_b32_e64 v70, v143, v212, s[80:81]
	s_and_b64 s[82:83], s[2:3], s[46:47]
	v_add_f32_e32 v213, v71, v213
	v_cndmask_b32_e64 v71, v143, v213, s[82:83]
	s_and_b64 s[80:81], s[2:3], s[40:41]
	v_add_f32_e32 v214, v72, v214
	v_cndmask_b32_e64 v72, v143, v214, s[80:81]
	s_and_b64 s[82:83], s[2:3], s[30:31]
	v_add_f32_e32 v215, v73, v215
	v_cndmask_b32_e64 v73, v143, v215, s[82:83]
	s_and_b64 s[80:81], s[2:3], s[18:19]
	v_add_f32_e32 v216, v74, v216
	v_cndmask_b32_e64 v74, v143, v216, s[80:81]
	s_and_b64 s[82:83], s[2:3], s[76:77]
	v_add_f32_e32 v217, v75, v217
	v_cndmask_b32_e64 v75, v143, v217, s[82:83]
	s_and_b64 s[80:81], s[2:3], s[16:17]
	v_add_f32_e32 v218, v76, v218
	v_cndmask_b32_e64 v76, v143, v218, s[80:81]
	s_and_b64 s[82:83], s[2:3], s[28:29]
	v_add_f32_e32 v219, v77, v219
	v_cndmask_b32_e64 v77, v143, v219, s[82:83]
	s_and_b64 s[80:81], s[2:3], s[44:45]
	v_add_f32_e32 v220, v78, v220
	v_cndmask_b32_e64 v78, v143, v220, s[80:81]
	s_and_b64 s[82:83], s[2:3], s[36:37]
	v_add_f32_e32 v221, v79, v221
	v_cndmask_b32_e64 v79, v143, v221, s[82:83]
	s_and_b64 s[80:81], s[2:3], s[24:25]
	v_add_f32_e32 v222, v80, v222
	v_cndmask_b32_e64 v80, v143, v222, s[80:81]
	s_and_b64 s[82:83], s[2:3], s[78:79]
	v_add_f32_e32 v223, v81, v223
	v_cndmask_b32_e64 v67, v143, v223, s[82:83]
	v_max_f32_e32 v66, v0, v0
	v_max_f32_e32 v81, v173, v173
	v_max_f32_e32 v66, v81, v66
	v_max3_f32 v66, v66, v83, v82
	v_max3_f32 v66, v66, v85, v84
	v_max3_f32 v66, v66, v87, v86
	v_max3_f32 v66, v66, v89, v88
	v_max3_f32 v66, v66, v91, v90
	v_max3_f32 v66, v66, v93, v92
	v_max3_f32 v66, v66, v95, v94
	v_max3_f32 v66, v66, v97, v96
	v_max3_f32 v66, v66, v68, v69
	v_max3_f32 v66, v66, v70, v71
	v_max3_f32 v66, v66, v72, v73
	v_max3_f32 v66, v66, v74, v75
	v_max3_f32 v66, v66, v76, v77
	v_max3_f32 v66, v66, v78, v79
	v_max3_f32 v66, v66, v80, v67
	v_mov_b32_e32 v81, v66
	s_nop 1
	v_permlane32_swap_b32_e32 v66, v81
	v_max_f32_e32 v81, v81, v81
	v_max_f32_e32 v66, v66, v66
	v_max_f32_e32 v66, v66, v81
	v_add_f32_e32 v66, 0, v66
	v_max_f32_e32 v81, v159, v159
	v_max_f32_e32 v81, v81, v66
	v_sub_f32_e32 v174, v66, v159
	v_sub_f32_e32 v66, v159, v81
	v_mul_f32_e32 v66, 0x3e0293ee, v66
	v_exp_f32_e32 v66, v66
	s_mov_b32 s2, 0x42b504f3
	v_cmp_ge_f32_e32 vcc, s2, v174
	s_cmp_eq_u64 vcc, exec
	s_cselect_b64 s[68:69], -1, 0
	v_cndmask_b32_e64 v66, v66, 1.0, s[68:69]
	v_cmp_gt_f32_e32 vcc, 1.0, v66
	s_cbranch_vccz .LBB0_1611
	s_mov_b64 s[2:3], exec
	v_readlane_b32 s12, v254, 38
	v_readlane_b32 s13, v254, 39
	s_and_b64 s[12:13], s[2:3], s[12:13]
	s_mov_b64 exec, s[12:13]
	s_cbranch_execz .LBB0_1610
	ds_write_b32 v157, v66 offset:128
	s_branch .LBB0_1610

; #define GAS __attribute__((address_space(1)))
; #define TAB(i) uni_ptr((gfp)__builtin_nontemporal_load(&tab[i]))
; __global__ void __launch_bounds__(NTHREADS, 2) mk_fwd(Args args) {
;     ...
;     if (IN(15)) {
;         PH_IDS
;         gfp ln_final = TAB(3);
;         f32x4 gfin[8];
; #pragma unroll
;         for (int j = 0; j < 8; ++j) gfin[j] = ((const GAS f32x4*)ln_final)[64 * j + lane];
;         for (int row = gw; row < MT; row += ngw) {
;             f32x4* hr = (f32x4*)(H + (size_t)row * DM) + lane;
;             const float rs = __builtin_amdgcn_rsqf(ss[4 * MT + row] * (1.0f / DM) + RMS_EPS);
;             f32x4 hv[8];
; #pragma unroll
;             for (int j = 0; j < 8; ++j) hv[j] = hr[64 * j];
; #pragma unroll
;             for (int j = 0; j < 8; ++j) __builtin_nontemporal_store(hv[j] * rs * gfin[j], &hr[64 * j]);
;         }
.LBB0_2264:
	v_readlane_b32 s2, v254, 11
	v_readlane_b32 s3, v254, 12
	s_cmp_lt_i32 s2, 16
	s_cselect_b64 s[2:3], -1, 0
	s_and_b64 s[0:1], s[2:3], s[0:1]
	s_andn2_b64 vcc, exec, s[0:1]
	s_cbranch_vccnz .LBB0_2268
	v_readlane_b32 s0, v254, 7
	s_waitcnt vmcnt(0)
	v_mov_b32_e32 v0, 0
	s_waitcnt lgkmcnt(0)
	v_mov_b32_e32 v1, 0x80000
	v_readlane_b32 s2, v254, 9
	v_readlane_b32 s3, v254, 10
	v_readlane_b32 s0, v254, 1
	v_mbcnt_lo_u32_b32 v0, -1, v0
	v_mbcnt_hi_u32_b32 v0, -1, v0
	v_readlane_b32 s1, v254, 8
	s_nop 0
	global_load_dwordx2 v[2:3], v1, s[2:3] offset:24 nt
	v_add_u32_e32 v1, s0, v0
	s_lshl_b32 s2, s69, 3
	v_readfirstlane_b32 s0, v1
	s_ashr_i32 s3, s0, 6
	s_add_i32 s6, s3, s2
	v_mov_b32_e32 v33, 0
	s_cmpk_gt_i32 s6, 0x3fff
	s_waitcnt vmcnt(0)
	v_readfirstlane_b32 s1, v3
	v_readfirstlane_b32 s0, v2
	s_cbranch_scc1 .LBB0_2268
	v_and_b32_e32 v0, 63, v0
	v_lshlrev_b32_e32 v32, 4, v0
	v_lshl_add_u64 v[16:17], s[0:1], 0, v[32:33]
	v_add_co_u32_e32 v34, vcc, 0x1000, v16
	global_load_dwordx4 v[0:3], v32, s[0:1]
	global_load_dwordx4 v[4:7], v32, s[0:1] offset:1024
	global_load_dwordx4 v[8:11], v32, s[0:1] offset:2048
	global_load_dwordx4 v[12:15], v32, s[0:1] offset:3072
	v_addc_co_u32_e32 v35, vcc, 0, v17, vcc
	global_load_dwordx4 v[16:19], v[34:35], off
	global_load_dwordx4 v[20:23], v[34:35], off offset:1024
	global_load_dwordx4 v[24:27], v[34:35], off offset:2048
	global_load_dwordx4 v[28:31], v[34:35], off offset:3072
	s_ashr_i32 s0, s3, 31
	s_ashr_i32 s1, s2, 31
	s_add_u32 s4, s3, s2
	s_addc_u32 s5, s0, s1
	v_readlane_b32 s8, v254, 7
	s_lshl_b64 s[0:1], s[4:5], 2
	v_readlane_b32 s10, v254, 9
	v_readlane_b32 s11, v254, 10
	s_add_u32 s0, s10, s0
	s_addc_u32 s1, s11, s1
	s_add_u32 s0, s0, 0x40000
	s_addc_u32 s1, s1, 0
	s_ashr_i32 s71, s70, 31
	s_lshl_b64 s[2:3], s[70:71], 2
	s_lshl_b64 s[4:5], s[4:5], 13
	v_readlane_b32 s9, v254, 8
	s_add_u32 s4, s8, s4
	s_addc_u32 s5, s9, s5
	v_lshl_add_u64 v[34:35], s[4:5], 0, v[32:33]
	s_mov_b64 s[4:5], 0x1c00
	v_lshl_add_u64 v[34:35], v[34:35], 0, s[4:5]
	s_lshl_b64 s[4:5], s[70:71], 13
	v_mov_b32_e32 v32, 0x358637bd
	v_add_co_u32_e32 v108, vcc, 0xfffff400, v34
	s_nop 1
	v_addc_co_u32_e32 v109, vcc, -1, v35, vcc
	global_load_dword v70, v33, s[0:1]
	v_mov_b32_e32 v34, v108
	v_mov_b32_e32 v35, v109
	global_load_dwordx4 v[36:39], v[34:35], off offset:-4096
	global_load_dwordx4 v[40:43], v[34:35], off offset:-3072
	global_load_dwordx4 v[44:47], v[34:35], off offset:-2048
	global_load_dwordx4 v[48:51], v[34:35], off offset:-1024
	global_load_dwordx4 v[52:55], v[34:35], off
	global_load_dwordx4 v[56:59], v[34:35], off offset:1024
	global_load_dwordx4 v[60:63], v[34:35], off offset:2048
	global_load_dwordx4 v[64:67], v[34:35], off offset:3072
	v_lshl_add_u64 v[108:109], v[108:109], 0, s[4:5]
	s_add_u32 s0, s0, s2
	s_addc_u32 s1, s1, s3
	s_add_i32 s6, s6, s70
	s_cmpk_lt_i32 s6, 0x4000
	s_cbranch_scc0 .Lfn_tail_a
	global_load_dword v104, v33, s[0:1]
	v_mov_b32_e32 v106, v108
	v_mov_b32_e32 v107, v109
	global_load_dwordx4 v[72:75], v[106:107], off offset:-4096
	global_load_dwordx4 v[76:79], v[106:107], off offset:-3072
	global_load_dwordx4 v[80:83], v[106:107], off offset:-2048
	global_load_dwordx4 v[84:87], v[106:107], off offset:-1024
	global_load_dwordx4 v[88:91], v[106:107], off
	global_load_dwordx4 v[92:95], v[106:107], off offset:1024
	global_load_dwordx4 v[96:99], v[106:107], off offset:2048
	global_load_dwordx4 v[100:103], v[106:107], off offset:3072
	v_lshl_add_u64 v[108:109], v[108:109], 0, s[4:5]
	s_add_u32 s0, s0, s2
	s_addc_u32 s1, s1, s3
	s_add_i32 s6, s6, s70
	s_waitcnt vmcnt(9)
	v_fmamk_f32 v70, v70, 0x3a000000, v32
	v_rsq_f32_e32 v70, v70
	s_nop 0
	v_pk_mul_f32 v[36:37], v[70:71], v[36:37] op_sel_hi:[0,1]
	v_pk_mul_f32 v[38:39], v[70:71], v[38:39] op_sel_hi:[0,1]
	v_pk_mul_f32 v[40:41], v[70:71], v[40:41] op_sel_hi:[0,1]
	v_pk_mul_f32 v[42:43], v[70:71], v[42:43] op_sel_hi:[0,1]
	v_pk_mul_f32 v[44:45], v[70:71], v[44:45] op_sel_hi:[0,1]
	v_pk_mul_f32 v[46:47], v[70:71], v[46:47] op_sel_hi:[0,1]
	v_pk_mul_f32 v[48:49], v[70:71], v[48:49] op_sel_hi:[0,1]
	v_pk_mul_f32 v[50:51], v[70:71], v[50:51] op_sel_hi:[0,1]
	v_pk_mul_f32 v[52:53], v[70:71], v[52:53] op_sel_hi:[0,1]
	v_pk_mul_f32 v[54:55], v[70:71], v[54:55] op_sel_hi:[0,1]
	v_pk_mul_f32 v[56:57], v[70:71], v[56:57] op_sel_hi:[0,1]
	v_pk_mul_f32 v[58:59], v[70:71], v[58:59] op_sel_hi:[0,1]
	v_pk_mul_f32 v[60:61], v[70:71], v[60:61] op_sel_hi:[0,1]
	v_pk_mul_f32 v[62:63], v[70:71], v[62:63] op_sel_hi:[0,1]
	v_pk_mul_f32 v[64:65], v[70:71], v[64:65] op_sel_hi:[0,1]
	v_pk_mul_f32 v[66:67], v[70:71], v[66:67] op_sel_hi:[0,1]
	v_pk_mul_f32 v[36:37], v[36:37], v[0:1]
	v_pk_mul_f32 v[38:39], v[38:39], v[2:3]
	v_pk_mul_f32 v[40:41], v[40:41], v[4:5]
	v_pk_mul_f32 v[42:43], v[42:43], v[6:7]
	v_pk_mul_f32 v[44:45], v[44:45], v[8:9]
	v_pk_mul_f32 v[46:47], v[46:47], v[10:11]
	v_pk_mul_f32 v[48:49], v[48:49], v[12:13]
	v_pk_mul_f32 v[50:51], v[50:51], v[14:15]
	v_pk_mul_f32 v[52:53], v[52:53], v[16:17]
	v_pk_mul_f32 v[54:55], v[54:55], v[18:19]
	v_pk_mul_f32 v[56:57], v[56:57], v[20:21]
	v_pk_mul_f32 v[58:59], v[58:59], v[22:23]
	v_pk_mul_f32 v[60:61], v[60:61], v[24:25]
	v_pk_mul_f32 v[62:63], v[62:63], v[26:27]
	v_pk_mul_f32 v[64:65], v[64:65], v[28:29]
	v_pk_mul_f32 v[66:67], v[66:67], v[30:31]
	global_store_dwordx4 v[34:35], v[36:39], off offset:-4096 nt
	global_store_dwordx4 v[34:35], v[40:43], off offset:-3072 nt
	global_store_dwordx4 v[34:35], v[44:47], off offset:-2048 nt
	global_store_dwordx4 v[34:35], v[48:51], off offset:-1024 nt
	global_store_dwordx4 v[34:35], v[52:55], off nt
	global_store_dwordx4 v[34:35], v[56:59], off offset:1024 nt
	global_store_dwordx4 v[34:35], v[60:63], off offset:2048 nt
	global_store_dwordx4 v[34:35], v[64:67], off offset:3072 nt
; __global__ void __launch_bounds__(NTHREADS, 2) mk_fwd(Args args) {
;     ...
;         for (int row = gw; row < MT; row += ngw) {
;             f32x4* hr = (f32x4*)(H + (size_t)row * DM) + lane;
;             const float rs = __builtin_amdgcn_rsqf(ss[4 * MT + row] * (1.0f / DM) + RMS_EPS);
;             f32x4 hv[8];
; #pragma unroll
;             for (int j = 0; j < 8; ++j) hv[j] = hr[64 * j];
; #pragma unroll
;             for (int j = 0; j < 8; ++j) __builtin_nontemporal_store(hv[j] * rs * gfin[j], &hr[64 * j]);
;         }
.Lfn_loop:
	s_cmpk_lt_i32 s6, 0x4000
	s_cbranch_scc0 .Lfn_tail_b
	global_load_dword v70, v33, s[0:1]
	v_mov_b32_e32 v34, v108
	v_mov_b32_e32 v35, v109
	global_load_dwordx4 v[36:39], v[34:35], off offset:-4096
	global_load_dwordx4 v[40:43], v[34:35], off offset:-3072
	global_load_dwordx4 v[44:47], v[34:35], off offset:-2048
	global_load_dwordx4 v[48:51], v[34:35], off offset:-1024
	global_load_dwordx4 v[52:55], v[34:35], off
	global_load_dwordx4 v[56:59], v[34:35], off offset:1024
	global_load_dwordx4 v[60:63], v[34:35], off offset:2048
	global_load_dwordx4 v[64:67], v[34:35], off offset:3072
	v_lshl_add_u64 v[108:109], v[108:109], 0, s[4:5]
	s_add_u32 s0, s0, s2
	s_addc_u32 s1, s1, s3
	s_add_i32 s6, s6, s70
	s_waitcnt vmcnt(17)
	v_fmamk_f32 v104, v104, 0x3a000000, v32
	v_rsq_f32_e32 v104, v104
	s_nop 0
	v_pk_mul_f32 v[72:73], v[104:105], v[72:73] op_sel_hi:[0,1]
	v_pk_mul_f32 v[74:75], v[104:105], v[74:75] op_sel_hi:[0,1]
	v_pk_mul_f32 v[76:77], v[104:105], v[76:77] op_sel_hi:[0,1]
	v_pk_mul_f32 v[78:79], v[104:105], v[78:79] op_sel_hi:[0,1]
	v_pk_mul_f32 v[80:81], v[104:105], v[80:81] op_sel_hi:[0,1]
	v_pk_mul_f32 v[82:83], v[104:105], v[82:83] op_sel_hi:[0,1]
	v_pk_mul_f32 v[84:85], v[104:105], v[84:85] op_sel_hi:[0,1]
	v_pk_mul_f32 v[86:87], v[104:105], v[86:87] op_sel_hi:[0,1]
	v_pk_mul_f32 v[88:89], v[104:105], v[88:89] op_sel_hi:[0,1]
	v_pk_mul_f32 v[90:91], v[104:105], v[90:91] op_sel_hi:[0,1]
	v_pk_mul_f32 v[92:93], v[104:105], v[92:93] op_sel_hi:[0,1]
	v_pk_mul_f32 v[94:95], v[104:105], v[94:95] op_sel_hi:[0,1]
	v_pk_mul_f32 v[96:97], v[104:105], v[96:97] op_sel_hi:[0,1]
	v_pk_mul_f32 v[98:99], v[104:105], v[98:99] op_sel_hi:[0,1]
	v_pk_mul_f32 v[100:101], v[104:105], v[100:101] op_sel_hi:[0,1]
	v_pk_mul_f32 v[102:103], v[104:105], v[102:103] op_sel_hi:[0,1]
	v_pk_mul_f32 v[72:73], v[72:73], v[0:1]
	v_pk_mul_f32 v[74:75], v[74:75], v[2:3]
	v_pk_mul_f32 v[76:77], v[76:77], v[4:5]
	v_pk_mul_f32 v[78:79], v[78:79], v[6:7]
	v_pk_mul_f32 v[80:81], v[80:81], v[8:9]
	v_pk_mul_f32 v[82:83], v[82:83], v[10:11]
	v_pk_mul_f32 v[84:85], v[84:85], v[12:13]
	v_pk_mul_f32 v[86:87], v[86:87], v[14:15]
	v_pk_mul_f32 v[88:89], v[88:89], v[16:17]
	v_pk_mul_f32 v[90:91], v[90:91], v[18:19]
	v_pk_mul_f32 v[92:93], v[92:93], v[20:21]
	v_pk_mul_f32 v[94:95], v[94:95], v[22:23]
	v_pk_mul_f32 v[96:97], v[96:97], v[24:25]
	v_pk_mul_f32 v[98:99], v[98:99], v[26:27]
	v_pk_mul_f32 v[100:101], v[100:101], v[28:29]
	v_pk_mul_f32 v[102:103], v[102:103], v[30:31]
	global_store_dwordx4 v[106:107], v[72:75], off offset:-4096 nt
	global_store_dwordx4 v[106:107], v[76:79], off offset:-3072 nt
	global_store_dwordx4 v[106:107], v[80:83], off offset:-2048 nt
	global_store_dwordx4 v[106:107], v[84:87], off offset:-1024 nt
	global_store_dwordx4 v[106:107], v[88:91], off nt
	global_store_dwordx4 v[106:107], v[92:95], off offset:1024 nt
	global_store_dwordx4 v[106:107], v[96:99], off offset:2048 nt
	global_store_dwordx4 v[106:107], v[100:103], off offset:3072 nt
	s_cmpk_lt_i32 s6, 0x4000
	s_cbranch_scc0 .Lfn_tail_a
	global_load_dword v104, v33, s[0:1]
	v_mov_b32_e32 v106, v108
	v_mov_b32_e32 v107, v109
	global_load_dwordx4 v[72:75], v[106:107], off offset:-4096
	global_load_dwordx4 v[76:79], v[106:107], off offset:-3072
	global_load_dwordx4 v[80:83], v[106:107], off offset:-2048
	global_load_dwordx4 v[84:87], v[106:107], off offset:-1024
	global_load_dwordx4 v[88:91], v[106:107], off
	global_load_dwordx4 v[92:95], v[106:107], off offset:1024
	global_load_dwordx4 v[96:99], v[106:107], off offset:2048
	global_load_dwordx4 v[100:103], v[106:107], off offset:3072
	v_lshl_add_u64 v[108:109], v[108:109], 0, s[4:5]
	s_add_u32 s0, s0, s2
	s_addc_u32 s1, s1, s3
	s_add_i32 s6, s6, s70
	s_waitcnt vmcnt(17)
	v_fmamk_f32 v70, v70, 0x3a000000, v32
	v_rsq_f32_e32 v70, v70
	s_nop 0
	v_pk_mul_f32 v[36:37], v[70:71], v[36:37] op_sel_hi:[0,1]
	v_pk_mul_f32 v[38:39], v[70:71], v[38:39] op_sel_hi:[0,1]
	v_pk_mul_f32 v[40:41], v[70:71], v[40:41] op_sel_hi:[0,1]
	v_pk_mul_f32 v[42:43], v[70:71], v[42:43] op_sel_hi:[0,1]
	v_pk_mul_f32 v[44:45], v[70:71], v[44:45] op_sel_hi:[0,1]
	v_pk_mul_f32 v[46:47], v[70:71], v[46:47] op_sel_hi:[0,1]
	v_pk_mul_f32 v[48:49], v[70:71], v[48:49] op_sel_hi:[0,1]
	v_pk_mul_f32 v[50:51], v[70:71], v[50:51] op_sel_hi:[0,1]
	v_pk_mul_f32 v[52:53], v[70:71], v[52:53] op_sel_hi:[0,1]
	v_pk_mul_f32 v[54:55], v[70:71], v[54:55] op_sel_hi:[0,1]
	v_pk_mul_f32 v[56:57], v[70:71], v[56:57] op_sel_hi:[0,1]
	v_pk_mul_f32 v[58:59], v[70:71], v[58:59] op_sel_hi:[0,1]
	v_pk_mul_f32 v[60:61], v[70:71], v[60:61] op_sel_hi:[0,1]
	v_pk_mul_f32 v[62:63], v[70:71], v[62:63] op_sel_hi:[0,1]
	v_pk_mul_f32 v[64:65], v[70:71], v[64:65] op_sel_hi:[0,1]
	v_pk_mul_f32 v[66:67], v[70:71], v[66:67] op_sel_hi:[0,1]
	v_pk_mul_f32 v[36:37], v[36:37], v[0:1]
	v_pk_mul_f32 v[38:39], v[38:39], v[2:3]
	v_pk_mul_f32 v[40:41], v[40:41], v[4:5]
	v_pk_mul_f32 v[42:43], v[42:43], v[6:7]
	v_pk_mul_f32 v[44:45], v[44:45], v[8:9]
	v_pk_mul_f32 v[46:47], v[46:47], v[10:11]
	v_pk_mul_f32 v[48:49], v[48:49], v[12:13]
	v_pk_mul_f32 v[50:51], v[50:51], v[14:15]
	v_pk_mul_f32 v[52:53], v[52:53], v[16:17]
	v_pk_mul_f32 v[54:55], v[54:55], v[18:19]
	v_pk_mul_f32 v[56:57], v[56:57], v[20:21]
	v_pk_mul_f32 v[58:59], v[58:59], v[22:23]
	v_pk_mul_f32 v[60:61], v[60:61], v[24:25]
	v_pk_mul_f32 v[62:63], v[62:63], v[26:27]
	v_pk_mul_f32 v[64:65], v[64:65], v[28:29]
	v_pk_mul_f32 v[66:67], v[66:67], v[30:31]
	global_store_dwordx4 v[34:35], v[36:39], off offset:-4096 nt
	global_store_dwordx4 v[34:35], v[40:43], off offset:-3072 nt
	global_store_dwordx4 v[34:35], v[44:47], off offset:-2048 nt
	global_store_dwordx4 v[34:35], v[48:51], off offset:-1024 nt
	global_store_dwordx4 v[34:35], v[52:55], off nt
	global_store_dwordx4 v[34:35], v[56:59], off offset:1024 nt
	global_store_dwordx4 v[34:35], v[60:63], off offset:2048 nt
	global_store_dwordx4 v[34:35], v[64:67], off offset:3072 nt
	s_branch .Lfn_loop
; __global__ void __launch_bounds__(NTHREADS, 2) mk_fwd(Args args) {
;     ...
;         for (int row = gw; row < MT; row += ngw) {
;             f32x4* hr = (f32x4*)(H + (size_t)row * DM) + lane;
;             const float rs = __builtin_amdgcn_rsqf(ss[4 * MT + row] * (1.0f / DM) + RMS_EPS);
;             f32x4 hv[8];
; #pragma unroll
;             for (int j = 0; j < 8; ++j) hv[j] = hr[64 * j];
; #pragma unroll
;             for (int j = 0; j < 8; ++j) __builtin_nontemporal_store(hv[j] * rs * gfin[j], &hr[64 * j]);
;         }
.Lfn_tail_a:
	s_waitcnt vmcnt(0)
	v_fmamk_f32 v70, v70, 0x3a000000, v32
	v_rsq_f32_e32 v70, v70
	s_nop 0
	v_pk_mul_f32 v[36:37], v[70:71], v[36:37] op_sel_hi:[0,1]
	v_pk_mul_f32 v[38:39], v[70:71], v[38:39] op_sel_hi:[0,1]
	v_pk_mul_f32 v[40:41], v[70:71], v[40:41] op_sel_hi:[0,1]
	v_pk_mul_f32 v[42:43], v[70:71], v[42:43] op_sel_hi:[0,1]
	v_pk_mul_f32 v[44:45], v[70:71], v[44:45] op_sel_hi:[0,1]
	v_pk_mul_f32 v[46:47], v[70:71], v[46:47] op_sel_hi:[0,1]
	v_pk_mul_f32 v[48:49], v[70:71], v[48:49] op_sel_hi:[0,1]
	v_pk_mul_f32 v[50:51], v[70:71], v[50:51] op_sel_hi:[0,1]
	v_pk_mul_f32 v[52:53], v[70:71], v[52:53] op_sel_hi:[0,1]
	v_pk_mul_f32 v[54:55], v[70:71], v[54:55] op_sel_hi:[0,1]
	v_pk_mul_f32 v[56:57], v[70:71], v[56:57] op_sel_hi:[0,1]
	v_pk_mul_f32 v[58:59], v[70:71], v[58:59] op_sel_hi:[0,1]
	v_pk_mul_f32 v[60:61], v[70:71], v[60:61] op_sel_hi:[0,1]
	v_pk_mul_f32 v[62:63], v[70:71], v[62:63] op_sel_hi:[0,1]
	v_pk_mul_f32 v[64:65], v[70:71], v[64:65] op_sel_hi:[0,1]
	v_pk_mul_f32 v[66:67], v[70:71], v[66:67] op_sel_hi:[0,1]
	v_pk_mul_f32 v[36:37], v[36:37], v[0:1]
	v_pk_mul_f32 v[38:39], v[38:39], v[2:3]
	v_pk_mul_f32 v[40:41], v[40:41], v[4:5]
	v_pk_mul_f32 v[42:43], v[42:43], v[6:7]
	v_pk_mul_f32 v[44:45], v[44:45], v[8:9]
	v_pk_mul_f32 v[46:47], v[46:47], v[10:11]
	v_pk_mul_f32 v[48:49], v[48:49], v[12:13]
	v_pk_mul_f32 v[50:51], v[50:51], v[14:15]
	v_pk_mul_f32 v[52:53], v[52:53], v[16:17]
	v_pk_mul_f32 v[54:55], v[54:55], v[18:19]
	v_pk_mul_f32 v[56:57], v[56:57], v[20:21]
	v_pk_mul_f32 v[58:59], v[58:59], v[22:23]
	v_pk_mul_f32 v[60:61], v[60:61], v[24:25]
	v_pk_mul_f32 v[62:63], v[62:63], v[26:27]
	v_pk_mul_f32 v[64:65], v[64:65], v[28:29]
	v_pk_mul_f32 v[66:67], v[66:67], v[30:31]
	global_store_dwordx4 v[34:35], v[36:39], off offset:-4096 nt
	global_store_dwordx4 v[34:35], v[40:43], off offset:-3072 nt
	global_store_dwordx4 v[34:35], v[44:47], off offset:-2048 nt
	global_store_dwordx4 v[34:35], v[48:51], off offset:-1024 nt
	global_store_dwordx4 v[34:35], v[52:55], off nt
	global_store_dwordx4 v[34:35], v[56:59], off offset:1024 nt
	global_store_dwordx4 v[34:35], v[60:63], off offset:2048 nt
	global_store_dwordx4 v[34:35], v[64:67], off offset:3072 nt
	s_branch .LBB0_2268
.Lfn_tail_b:
	s_waitcnt vmcnt(0)
	v_fmamk_f32 v104, v104, 0x3a000000, v32
	v_rsq_f32_e32 v104, v104
	s_nop 0
	v_pk_mul_f32 v[72:73], v[104:105], v[72:73] op_sel_hi:[0,1]
	v_pk_mul_f32 v[74:75], v[104:105], v[74:75] op_sel_hi:[0,1]
	v_pk_mul_f32 v[76:77], v[104:105], v[76:77] op_sel_hi:[0,1]
	v_pk_mul_f32 v[78:79], v[104:105], v[78:79] op_sel_hi:[0,1]
	v_pk_mul_f32 v[80:81], v[104:105], v[80:81] op_sel_hi:[0,1]
	v_pk_mul_f32 v[82:83], v[104:105], v[82:83] op_sel_hi:[0,1]
	v_pk_mul_f32 v[84:85], v[104:105], v[84:85] op_sel_hi:[0,1]
	v_pk_mul_f32 v[86:87], v[104:105], v[86:87] op_sel_hi:[0,1]
	v_pk_mul_f32 v[88:89], v[104:105], v[88:89] op_sel_hi:[0,1]
	v_pk_mul_f32 v[90:91], v[104:105], v[90:91] op_sel_hi:[0,1]
	v_pk_mul_f32 v[92:93], v[104:105], v[92:93] op_sel_hi:[0,1]
	v_pk_mul_f32 v[94:95], v[104:105], v[94:95] op_sel_hi:[0,1]
	v_pk_mul_f32 v[96:97], v[104:105], v[96:97] op_sel_hi:[0,1]
	v_pk_mul_f32 v[98:99], v[104:105], v[98:99] op_sel_hi:[0,1]
	v_pk_mul_f32 v[100:101], v[104:105], v[100:101] op_sel_hi:[0,1]
	v_pk_mul_f32 v[102:103], v[104:105], v[102:103] op_sel_hi:[0,1]
	v_pk_mul_f32 v[72:73], v[72:73], v[0:1]
	v_pk_mul_f32 v[74:75], v[74:75], v[2:3]
	v_pk_mul_f32 v[76:77], v[76:77], v[4:5]
	v_pk_mul_f32 v[78:79], v[78:79], v[6:7]
	v_pk_mul_f32 v[80:81], v[80:81], v[8:9]
	v_pk_mul_f32 v[82:83], v[82:83], v[10:11]
	v_pk_mul_f32 v[84:85], v[84:85], v[12:13]
	v_pk_mul_f32 v[86:87], v[86:87], v[14:15]
	v_pk_mul_f32 v[88:89], v[88:89], v[16:17]
	v_pk_mul_f32 v[90:91], v[90:91], v[18:19]
	v_pk_mul_f32 v[92:93], v[92:93], v[20:21]
	v_pk_mul_f32 v[94:95], v[94:95], v[22:23]
	v_pk_mul_f32 v[96:97], v[96:97], v[24:25]
	v_pk_mul_f32 v[98:99], v[98:99], v[26:27]
	v_pk_mul_f32 v[100:101], v[100:101], v[28:29]
	v_pk_mul_f32 v[102:103], v[102:103], v[30:31]
	global_store_dwordx4 v[106:107], v[72:75], off offset:-4096 nt
	global_store_dwordx4 v[106:107], v[76:79], off offset:-3072 nt
	global_store_dwordx4 v[106:107], v[80:83], off offset:-2048 nt
	global_store_dwordx4 v[106:107], v[84:87], off offset:-1024 nt
	global_store_dwordx4 v[106:107], v[88:91], off nt
	global_store_dwordx4 v[106:107], v[92:95], off offset:1024 nt
	global_store_dwordx4 v[106:107], v[96:99], off offset:2048 nt
	global_store_dwordx4 v[106:107], v[100:103], off offset:3072 nt
